# attention work queue reordered (decode unit every 3rd slot of first 768) + side-GEMM epilogue row-stat loads batched (2 waits instead of 4) + Up side k-loop coalesced
# speedup vs baseline: 1.0043x; 1.0026x over previous
.LBB0_342:
	v_mov_b32_e32 v79, v2
	v_lshlrev_b64 v[72:73], 8, v[78:79]
	v_lshl_add_u64 v[84:85], s[44:45], 0, v[72:73]
	global_load_dwordx4 v[72:75], v[84:85], off offset:48
	global_load_dwordx4 v[90:93], v[84:85], off offset:32
	global_load_dwordx4 v[94:97], v[84:85], off
	global_load_dwordx4 v[98:101], v[84:85], off offset:16
	global_load_dwordx4 v[106:109], v[84:85], off offset:112
	global_load_dwordx4 v[110:113], v[84:85], off offset:96
	global_load_dwordx4 v[114:117], v[84:85], off offset:80
	global_load_dwordx4 v[118:121], v[84:85], off offset:64
	global_load_dwordx4 v[228:231], v[84:85], off offset:176
	global_load_dwordx4 v[232:235], v[84:85], off offset:160
	global_load_dwordx4 v[236:239], v[84:85], off offset:144
	global_load_dwordx4 v[240:243], v[84:85], off offset:128
	s_waitcnt vmcnt(8)
	v_pk_add_f32 v[96:97], v[96:97], v[100:101]
	v_pk_add_f32 v[94:95], v[94:95], v[98:99]
	v_pk_add_f32 v[92:93], v[96:97], v[92:93]
	v_pk_add_f32 v[90:91], v[94:95], v[90:91]
	v_pk_add_f32 v[102:103], v[92:93], v[74:75]
	v_pk_add_f32 v[104:105], v[90:91], v[72:73]
	global_load_dwordx4 v[72:75], v[84:85], off offset:240
	global_load_dwordx4 v[90:93], v[84:85], off offset:224
	global_load_dwordx4 v[94:97], v[84:85], off offset:208
	global_load_dwordx4 v[98:101], v[84:85], off offset:192
	s_waitcnt vmcnt(8)
	v_pk_add_f32 v[120:121], v[102:103], v[120:121]
	v_pk_add_f32 v[118:119], v[104:105], v[118:119]
	v_pk_add_f32 v[116:117], v[120:121], v[116:117]
	v_pk_add_f32 v[114:115], v[118:119], v[114:115]
	v_pk_add_f32 v[112:113], v[116:117], v[112:113]
	v_pk_add_f32 v[110:111], v[114:115], v[110:111]
	v_pk_add_f32 v[102:103], v[112:113], v[108:109]
	v_pk_add_f32 v[104:105], v[110:111], v[106:107]
	s_waitcnt vmcnt(4)
	v_pk_add_f32 v[242:243], v[102:103], v[242:243]
	v_pk_add_f32 v[240:241], v[104:105], v[240:241]
	v_pk_add_f32 v[238:239], v[242:243], v[238:239]
	v_pk_add_f32 v[236:237], v[240:241], v[236:237]
	v_pk_add_f32 v[234:235], v[238:239], v[234:235]
	v_pk_add_f32 v[232:233], v[236:237], v[232:233]
	v_pk_add_f32 v[102:103], v[234:235], v[230:231]
	v_pk_add_f32 v[104:105], v[232:233], v[228:229]
	s_waitcnt vmcnt(0)
	v_pk_add_f32 v[84:85], v[102:103], v[100:101]
	v_pk_add_f32 v[98:99], v[104:105], v[98:99]
	v_pk_add_f32 v[84:85], v[84:85], v[96:97]
	v_pk_add_f32 v[94:95], v[98:99], v[94:95]
	v_pk_add_f32 v[84:85], v[84:85], v[92:93]
	v_pk_add_f32 v[90:91], v[94:95], v[90:91]
	v_pk_add_f32 v[74:75], v[84:85], v[74:75]
	v_pk_add_f32 v[72:73], v[90:91], v[72:73]
	s_andn2_saveexec_b64 s[0:1], s[0:1]
	s_cbranch_execz .LBB0_335

.LBB0_599:
	ds_read_b128 v[64:67], v85
	ds_read_b128 v[68:71], v85 offset:9216
	ds_read_b128 v[60:63], v85 offset:18432
	ds_read_b128 v[56:59], v85 offset:27648
	ds_read_b128 v[52:55], v85 offset:36864
	ds_read_b128 v[48:51], v85 offset:46080
	ds_read_b128 v[44:47], v85 offset:55296
	ds_read_b128 v[40:43], v85 offset:64512
	v_add_u32_e32 v82, s9, v3
	v_cmp_lt_i32_e64 s[4:5], s48, v82
	s_and_saveexec_b64 s[0:1], s[4:5]
	s_xor_b64 s[0:1], exec, s[0:1]
	s_cbranch_execz .LBB0_601
	v_add_u32_e32 v72, 0xffff8000, v82
	v_mov_b32_e32 v73, v2
	v_lshlrev_b64 v[72:73], 8, v[72:73]
	v_lshl_add_u64 v[100:101], s[44:45], 0, v[72:73]
	global_load_dwordx4 v[72:75], v[100:101], off offset:48
	global_load_dwordx4 v[88:91], v[100:101], off offset:32
	global_load_dwordx4 v[92:95], v[100:101], off
	global_load_dwordx4 v[96:99], v[100:101], off offset:16
	global_load_dwordx4 v[106:109], v[100:101], off offset:112
	global_load_dwordx4 v[110:113], v[100:101], off offset:96
	global_load_dwordx4 v[114:117], v[100:101], off offset:80
	global_load_dwordx4 v[118:121], v[100:101], off offset:64
	global_load_dwordx4 v[228:231], v[100:101], off offset:176
	global_load_dwordx4 v[232:235], v[100:101], off offset:160
	global_load_dwordx4 v[236:239], v[100:101], off offset:144
	global_load_dwordx4 v[240:243], v[100:101], off offset:128
	v_mov_b32_e32 v83, v2
	s_waitcnt vmcnt(8)
	v_pk_add_f32 v[94:95], v[94:95], v[98:99]
	v_pk_add_f32 v[92:93], v[92:93], v[96:97]
	v_pk_add_f32 v[90:91], v[94:95], v[90:91]
	v_pk_add_f32 v[88:89], v[92:93], v[88:89]
	v_pk_add_f32 v[102:103], v[90:91], v[74:75]
	v_pk_add_f32 v[104:105], v[88:89], v[72:73]
	global_load_dwordx4 v[72:75], v[100:101], off offset:240
	global_load_dwordx4 v[88:91], v[100:101], off offset:224
	global_load_dwordx4 v[92:95], v[100:101], off offset:208
	global_load_dwordx4 v[96:99], v[100:101], off offset:192
	s_waitcnt vmcnt(8)
	v_pk_add_f32 v[120:121], v[102:103], v[120:121]
	v_pk_add_f32 v[118:119], v[104:105], v[118:119]
	v_pk_add_f32 v[116:117], v[120:121], v[116:117]
	v_pk_add_f32 v[114:115], v[118:119], v[114:115]
	v_pk_add_f32 v[112:113], v[116:117], v[112:113]
	v_pk_add_f32 v[110:111], v[114:115], v[110:111]
	v_pk_add_f32 v[102:103], v[112:113], v[108:109]
	v_pk_add_f32 v[104:105], v[110:111], v[106:107]
	s_waitcnt vmcnt(4)
	v_pk_add_f32 v[242:243], v[102:103], v[242:243]
	v_pk_add_f32 v[240:241], v[104:105], v[240:241]
	v_pk_add_f32 v[238:239], v[242:243], v[238:239]
	v_pk_add_f32 v[236:237], v[240:241], v[236:237]
	v_pk_add_f32 v[234:235], v[238:239], v[234:235]
	v_pk_add_f32 v[232:233], v[236:237], v[232:233]
	v_pk_add_f32 v[102:103], v[234:235], v[230:231]
	v_pk_add_f32 v[104:105], v[232:233], v[228:229]
	s_waitcnt vmcnt(0)
	v_pk_add_f32 v[98:99], v[102:103], v[98:99]
	v_pk_add_f32 v[96:97], v[104:105], v[96:97]
	v_pk_add_f32 v[94:95], v[98:99], v[94:95]
	v_pk_add_f32 v[92:93], v[96:97], v[92:93]
	v_pk_add_f32 v[90:91], v[94:95], v[90:91]
	v_pk_add_f32 v[88:89], v[92:93], v[88:89]
	v_pk_add_f32 v[74:75], v[90:91], v[74:75]
	v_pk_add_f32 v[72:73], v[88:89], v[72:73]

.LBB0_794:
	v_mov_b32_e32 v0, s89
	s_waitcnt lgkmcnt(0)
	s_barrier
	ds_read_b32 v0, v0
	s_mov_b64 s[0:1], -1
	s_waitcnt lgkmcnt(0)
	s_barrier
	v_readfirstlane_b32 s83, v0
	s_cmpk_gt_i32 s83, 0x507
	s_cbranch_scc1 .LBB0_787
	s_cmpk_gt_i32 s83, 0x2ff
	s_cbranch_scc1 .Latt_remap_done
	s_mul_hi_u32 s0, s83, 0xaaaaaaab
	s_lshr_b32 s0, s0, 1
	s_mul_i32 s1, s0, 3
	s_sub_i32 s1, s83, s1
	s_cmp_eq_u32 s1, 0
	s_cbranch_scc0 .Latt_remap_pre
	s_lshl_b32 s83, s0, 1
	s_or_b32 s83, s83, 1
	s_branch .Latt_remap_done
.Latt_remap_pre:
	s_sub_i32 s1, s83, s0
	s_add_i32 s1, s1, -1
	s_lshl_b32 s2, s1, 1
	s_add_i32 s3, s1, 0x100
	s_cmpk_lt_u32 s1, 0x100
	s_cselect_b32 s83, s2, s3
.Latt_remap_done:
	s_cmpk_gt_i32 s83, 0x1ff
	s_cselect_b64 s[12:13], -1, 0
	s_bitcmp0_b32 s83, 0
	s_cselect_b64 s[0:1], -1, 0
	s_or_b64 s[2:3], s[12:13], s[0:1]
	s_mov_b64 s[0:1], -1
	s_and_b64 vcc, exec, s[2:3]
	s_cbranch_vccnz .LBB0_913
	s_ashr_i32 s84, s83, 2
	s_add_i32 s8, s84, 0x8010
	v_mbcnt_lo_u32_b32 v3, -1, 0
	v_mbcnt_hi_u32_b32 v3, -1, v3
	s_ashr_i32 s9, s8, 31
	v_add_u32_e32 v0, s52, v3
	s_waitcnt vmcnt(3)
	v_ashrrev_i32_e32 v134, 6, v0
	s_lshl_b64 s[0:1], s[8:9], 11
	v_readfirstlane_b32 s14, v134
	s_add_u32 s2, s28, s0
	s_addc_u32 s3, s29, s1
	s_lshl_b32 s24, s14, 7
	s_ashr_i32 s25, s24, 31
	s_lshl_b64 s[0:1], s[24:25], 1
	v_and_b32_e32 v7, 31, v3
	s_add_u32 s0, s2, s0
	s_addc_u32 s1, s3, s1
	v_lshlrev_b32_e32 v1, 3, v7
	global_load_dwordx2 v[4:5], v1, s[0:1]
	s_mul_i32 s0, s14, 0x280
	s_add_i32 s0, s0, 0
	v_bfe_u32 v6, v3, 5, 1
	s_ashr_i32 s15, s14, 31
	s_add_i32 s0, s0, 0x15000
	v_lshl_add_u32 v138, v6, 1, s0
	s_lshl_b64 s[0:1], s[14:15], 9
	v_and_b32_e32 v159, 63, v3
	v_cmp_eq_u32_e64 s[4:5], 31, v7
	s_movk_i32 s2, 0xffe0
	s_waitcnt vmcnt(0)
	v_lshlrev_b32_e32 v1, 16, v4
	v_and_b32_e32 v135, 0xffff0000, v4
	v_lshlrev_b32_e32 v136, 16, v5
	v_and_b32_e32 v137, 0xffff0000, v5
	v_lshlrev_b32_e32 v4, 12, v6
	v_mov_b32_e32 v5, v2
	v_lshl_add_u64 v[4:5], v[4:5], 0, s[0:1]
	v_readlane_b32 s0, v255, 18
	v_lshl_or_b32 v4, v7, 4, v4
	v_readlane_b32 s1, v255, 19
	s_nop 1
	v_lshl_add_u64 v[132:133], s[0:1], 0, v[4:5]
	s_branch .LBB0_798

.LBB0_1139:
	ds_read_b128 v[64:67], v77
	ds_read_b128 v[68:71], v77 offset:9216
	ds_read_b128 v[60:63], v77 offset:18432
	ds_read_b128 v[56:59], v77 offset:27648
	ds_read_b128 v[52:55], v77 offset:36864
	ds_read_b128 v[48:51], v77 offset:46080
	ds_read_b128 v[44:47], v77 offset:55296
	ds_read_b128 v[40:43], v77 offset:64512
	v_add_u32_e32 v88, 0x8000, v86
	v_cmp_lt_i32_e32 vcc, s48, v88
	s_and_saveexec_b64 s[0:1], vcc
	s_xor_b64 s[0:1], exec, s[0:1]
	s_cbranch_execz .LBB0_1141
	v_mov_b32_e32 v87, v2
	v_lshlrev_b64 v[72:73], 8, v[86:87]
	v_lshl_add_u64 v[104:105], s[96:97], 0, v[72:73]
	global_load_dwordx4 v[72:75], v[104:105], off offset:48
	global_load_dwordx4 v[92:95], v[104:105], off offset:32
	global_load_dwordx4 v[96:99], v[104:105], off
	global_load_dwordx4 v[100:103], v[104:105], off offset:16
	global_load_dwordx4 v[110:113], v[104:105], off offset:112
	global_load_dwordx4 v[114:117], v[104:105], off offset:96
	global_load_dwordx4 v[118:121], v[104:105], off offset:80
	global_load_dwordx4 v[228:231], v[104:105], off offset:64
	global_load_dwordx4 v[232:235], v[104:105], off offset:176
	global_load_dwordx4 v[236:239], v[104:105], off offset:160
	global_load_dwordx4 v[240:243], v[104:105], off offset:144
	global_load_dwordx4 v[244:247], v[104:105], off offset:128
	v_mov_b32_e32 v89, v2
	s_waitcnt vmcnt(8)
	v_pk_add_f32 v[98:99], v[98:99], v[102:103]
	v_pk_add_f32 v[96:97], v[96:97], v[100:101]
	v_pk_add_f32 v[94:95], v[98:99], v[94:95]
	v_pk_add_f32 v[92:93], v[96:97], v[92:93]
	v_pk_add_f32 v[106:107], v[94:95], v[74:75]
	v_pk_add_f32 v[108:109], v[92:93], v[72:73]
	global_load_dwordx4 v[72:75], v[104:105], off offset:240
	global_load_dwordx4 v[92:95], v[104:105], off offset:224
	global_load_dwordx4 v[96:99], v[104:105], off offset:208
	global_load_dwordx4 v[100:103], v[104:105], off offset:192
	s_waitcnt vmcnt(8)
	v_pk_add_f32 v[230:231], v[106:107], v[230:231]
	v_pk_add_f32 v[228:229], v[108:109], v[228:229]
	v_pk_add_f32 v[120:121], v[230:231], v[120:121]
	v_pk_add_f32 v[118:119], v[228:229], v[118:119]
	v_pk_add_f32 v[116:117], v[120:121], v[116:117]
	v_pk_add_f32 v[114:115], v[118:119], v[114:115]
	v_pk_add_f32 v[106:107], v[116:117], v[112:113]
	v_pk_add_f32 v[108:109], v[114:115], v[110:111]
	s_waitcnt vmcnt(4)
	v_pk_add_f32 v[246:247], v[106:107], v[246:247]
	v_pk_add_f32 v[244:245], v[108:109], v[244:245]
	v_pk_add_f32 v[242:243], v[246:247], v[242:243]
	v_pk_add_f32 v[240:241], v[244:245], v[240:241]
	v_pk_add_f32 v[238:239], v[242:243], v[238:239]
	v_pk_add_f32 v[236:237], v[240:241], v[236:237]
	v_pk_add_f32 v[106:107], v[238:239], v[234:235]
	v_pk_add_f32 v[108:109], v[236:237], v[232:233]
	s_waitcnt vmcnt(0)
	v_pk_add_f32 v[102:103], v[106:107], v[102:103]
	v_pk_add_f32 v[100:101], v[108:109], v[100:101]
	v_pk_add_f32 v[98:99], v[102:103], v[98:99]
	v_pk_add_f32 v[96:97], v[100:101], v[96:97]
	v_pk_add_f32 v[94:95], v[98:99], v[94:95]
	v_pk_add_f32 v[92:93], v[96:97], v[92:93]
	v_pk_add_f32 v[74:75], v[94:95], v[74:75]
	v_pk_add_f32 v[72:73], v[92:93], v[72:73]

.LBB0_2324:
	ds_read_b128 v[64:67], v84
	ds_read_b128 v[68:71], v84 offset:9216
	ds_read_b128 v[60:63], v84 offset:18432
	ds_read_b128 v[56:59], v84 offset:27648
	ds_read_b128 v[52:55], v84 offset:36864
	ds_read_b128 v[48:51], v84 offset:46080
	ds_read_b128 v[44:47], v84 offset:55296
	ds_read_b128 v[40:43], v84 offset:64512
	v_add_u32_e32 v82, 0x8000, v78
	v_cmp_lt_i32_e32 vcc, s48, v82
	s_and_saveexec_b64 s[0:1], vcc
	s_xor_b64 s[0:1], exec, s[0:1]
	s_cbranch_execz .LBB0_2326
	v_mov_b32_e32 v79, v2
	v_lshlrev_b64 v[72:73], 8, v[78:79]
	v_lshl_add_u64 v[100:101], s[34:35], 0, v[72:73]
	global_load_dwordx4 v[72:75], v[100:101], off offset:48
	global_load_dwordx4 v[88:91], v[100:101], off offset:32
	global_load_dwordx4 v[92:95], v[100:101], off
	global_load_dwordx4 v[96:99], v[100:101], off offset:16
	global_load_dwordx4 v[106:109], v[100:101], off offset:112
	global_load_dwordx4 v[110:113], v[100:101], off offset:96
	global_load_dwordx4 v[114:117], v[100:101], off offset:80
	global_load_dwordx4 v[118:121], v[100:101], off offset:64
	global_load_dwordx4 v[234:237], v[100:101], off offset:176
	global_load_dwordx4 v[238:241], v[100:101], off offset:160
	global_load_dwordx4 v[242:245], v[100:101], off offset:144
	global_load_dwordx4 v[246:249], v[100:101], off offset:128
	v_mov_b32_e32 v83, v2
	s_waitcnt vmcnt(8)
	v_pk_add_f32 v[94:95], v[94:95], v[98:99]
	v_pk_add_f32 v[92:93], v[92:93], v[96:97]
	v_pk_add_f32 v[90:91], v[94:95], v[90:91]
	v_pk_add_f32 v[88:89], v[92:93], v[88:89]
	v_pk_add_f32 v[102:103], v[90:91], v[74:75]
	v_pk_add_f32 v[104:105], v[88:89], v[72:73]
	global_load_dwordx4 v[72:75], v[100:101], off offset:240
	global_load_dwordx4 v[88:91], v[100:101], off offset:224
	global_load_dwordx4 v[92:95], v[100:101], off offset:208
	global_load_dwordx4 v[96:99], v[100:101], off offset:192
	s_waitcnt vmcnt(8)
	v_pk_add_f32 v[120:121], v[102:103], v[120:121]
	v_pk_add_f32 v[118:119], v[104:105], v[118:119]
	v_pk_add_f32 v[116:117], v[120:121], v[116:117]
	v_pk_add_f32 v[114:115], v[118:119], v[114:115]
	v_pk_add_f32 v[112:113], v[116:117], v[112:113]
	v_pk_add_f32 v[110:111], v[114:115], v[110:111]
	v_pk_add_f32 v[102:103], v[112:113], v[108:109]
	v_pk_add_f32 v[104:105], v[110:111], v[106:107]
	s_waitcnt vmcnt(4)
	v_pk_add_f32 v[248:249], v[102:103], v[248:249]
	v_pk_add_f32 v[246:247], v[104:105], v[246:247]
	v_pk_add_f32 v[244:245], v[248:249], v[244:245]
	v_pk_add_f32 v[242:243], v[246:247], v[242:243]
	v_pk_add_f32 v[240:241], v[244:245], v[240:241]
	v_pk_add_f32 v[238:239], v[242:243], v[238:239]
	v_pk_add_f32 v[102:103], v[240:241], v[236:237]
	v_pk_add_f32 v[104:105], v[238:239], v[234:235]
	s_waitcnt vmcnt(0)
	v_pk_add_f32 v[98:99], v[102:103], v[98:99]
	v_pk_add_f32 v[96:97], v[104:105], v[96:97]
	v_pk_add_f32 v[94:95], v[98:99], v[94:95]
	v_pk_add_f32 v[92:93], v[96:97], v[92:93]
	v_pk_add_f32 v[90:91], v[94:95], v[90:91]
	v_pk_add_f32 v[88:89], v[92:93], v[88:89]
	v_pk_add_f32 v[74:75], v[90:91], v[74:75]
	v_pk_add_f32 v[72:73], v[88:89], v[72:73]

.LBB0_2735:
	ds_read_b128 v[64:67], v77
	ds_read_b128 v[68:71], v77 offset:9216
	ds_read_b128 v[60:63], v77 offset:18432
	ds_read_b128 v[56:59], v77 offset:27648
	ds_read_b128 v[52:55], v77 offset:36864
	ds_read_b128 v[48:51], v77 offset:46080
	ds_read_b128 v[44:47], v77 offset:55296
	ds_read_b128 v[40:43], v77 offset:64512
	v_add_u32_e32 v90, s31, v3
	v_cmp_lt_i32_e64 s[8:9], s48, v90
	s_and_saveexec_b64 s[0:1], s[8:9]
	s_xor_b64 s[0:1], exec, s[0:1]
	s_cbranch_execz .LBB0_2737
	v_add_u32_e32 v72, 0xffff8000, v90
	v_mov_b32_e32 v73, v2
	v_lshlrev_b64 v[72:73], 8, v[72:73]
	v_lshl_add_u64 v[106:107], s[56:57], 0, v[72:73]
	global_load_dwordx4 v[72:75], v[106:107], off offset:48
	global_load_dwordx4 v[94:97], v[106:107], off offset:32
	global_load_dwordx4 v[98:101], v[106:107], off
	global_load_dwordx4 v[102:105], v[106:107], off offset:16
	global_load_dwordx4 v[112:115], v[106:107], off offset:112
	global_load_dwordx4 v[116:119], v[106:107], off offset:96
	global_load_dwordx4 v[228:231], v[106:107], off offset:80
	global_load_dwordx4 v[232:235], v[106:107], off offset:64
	global_load_dwordx4 v[236:239], v[106:107], off offset:176
	global_load_dwordx4 v[240:243], v[106:107], off offset:160
	global_load_dwordx4 v[244:247], v[106:107], off offset:144
	global_load_dwordx4 v[248:251], v[106:107], off offset:128
	s_waitcnt vmcnt(8)
	v_pk_add_f32 v[100:101], v[100:101], v[104:105]
	v_pk_add_f32 v[98:99], v[98:99], v[102:103]
	v_pk_add_f32 v[96:97], v[100:101], v[96:97]
	v_pk_add_f32 v[94:95], v[98:99], v[94:95]
	v_pk_add_f32 v[108:109], v[96:97], v[74:75]
	v_pk_add_f32 v[110:111], v[94:95], v[72:73]
	global_load_dwordx4 v[72:75], v[106:107], off offset:240
	global_load_dwordx4 v[94:97], v[106:107], off offset:224
	global_load_dwordx4 v[98:101], v[106:107], off offset:208
	global_load_dwordx4 v[102:105], v[106:107], off offset:192
	s_waitcnt vmcnt(8)
	v_pk_add_f32 v[234:235], v[108:109], v[234:235]
	v_pk_add_f32 v[232:233], v[110:111], v[232:233]
	v_pk_add_f32 v[230:231], v[234:235], v[230:231]
	v_pk_add_f32 v[228:229], v[232:233], v[228:229]
	v_pk_add_f32 v[118:119], v[230:231], v[118:119]
	v_pk_add_f32 v[116:117], v[228:229], v[116:117]
	v_pk_add_f32 v[108:109], v[118:119], v[114:115]
	v_pk_add_f32 v[110:111], v[116:117], v[112:113]
	s_waitcnt vmcnt(4)
	v_pk_add_f32 v[250:251], v[108:109], v[250:251]
	v_pk_add_f32 v[248:249], v[110:111], v[248:249]
	v_pk_add_f32 v[246:247], v[250:251], v[246:247]
	v_pk_add_f32 v[244:245], v[248:249], v[244:245]
	v_pk_add_f32 v[242:243], v[246:247], v[242:243]
	v_pk_add_f32 v[240:241], v[244:245], v[240:241]
	v_pk_add_f32 v[108:109], v[242:243], v[238:239]
	v_pk_add_f32 v[110:111], v[240:241], v[236:237]
	s_waitcnt vmcnt(0)
	v_pk_add_f32 v[104:105], v[108:109], v[104:105]
	v_pk_add_f32 v[102:103], v[110:111], v[102:103]
	v_pk_add_f32 v[100:101], v[104:105], v[100:101]
	v_pk_add_f32 v[98:99], v[102:103], v[98:99]
	v_pk_add_f32 v[96:97], v[100:101], v[96:97]
	v_pk_add_f32 v[94:95], v[98:99], v[94:95]
	v_pk_add_f32 v[74:75], v[96:97], v[74:75]
	v_pk_add_f32 v[72:73], v[94:95], v[72:73]

.LBB0_3432:
	ds_read_b128 v[64:67], v86
	ds_read_b128 v[68:71], v86 offset:9216
	ds_read_b128 v[60:63], v86 offset:18432
	ds_read_b128 v[56:59], v86 offset:27648
	ds_read_b128 v[52:55], v86 offset:36864
	ds_read_b128 v[48:51], v86 offset:46080
	ds_read_b128 v[44:47], v86 offset:55296
	ds_read_b128 v[40:43], v86 offset:64512
	v_add_u32_e32 v84, 0x8000, v82
	v_cmp_lt_i32_e32 vcc, s48, v84
	s_and_saveexec_b64 s[2:3], vcc
	s_xor_b64 s[2:3], exec, s[2:3]
	s_cbranch_execz .LBB0_3434
	v_mov_b32_e32 v83, v2
	v_lshlrev_b64 v[72:73], 8, v[82:83]
	v_lshl_add_u64 v[102:103], s[26:27], 0, v[72:73]
	global_load_dwordx4 v[72:75], v[102:103], off offset:48
	global_load_dwordx4 v[90:93], v[102:103], off offset:32
	global_load_dwordx4 v[94:97], v[102:103], off
	global_load_dwordx4 v[98:101], v[102:103], off offset:16
	global_load_dwordx4 v[108:111], v[102:103], off offset:112
	global_load_dwordx4 v[112:115], v[102:103], off offset:96
	global_load_dwordx4 v[116:119], v[102:103], off offset:80
	global_load_dwordx4 v[228:231], v[102:103], off offset:64
	global_load_dwordx4 v[232:235], v[102:103], off offset:176
	global_load_dwordx4 v[236:239], v[102:103], off offset:160
	global_load_dwordx4 v[240:243], v[102:103], off offset:144
	global_load_dwordx4 v[244:247], v[102:103], off offset:128
	v_mov_b32_e32 v85, v2
	s_waitcnt vmcnt(8)
	v_pk_add_f32 v[96:97], v[96:97], v[100:101]
	v_pk_add_f32 v[94:95], v[94:95], v[98:99]
	v_pk_add_f32 v[92:93], v[96:97], v[92:93]
	v_pk_add_f32 v[90:91], v[94:95], v[90:91]
	v_pk_add_f32 v[104:105], v[92:93], v[74:75]
	v_pk_add_f32 v[106:107], v[90:91], v[72:73]
	global_load_dwordx4 v[72:75], v[102:103], off offset:240
	global_load_dwordx4 v[90:93], v[102:103], off offset:224
	global_load_dwordx4 v[94:97], v[102:103], off offset:208
	global_load_dwordx4 v[98:101], v[102:103], off offset:192
	s_waitcnt vmcnt(8)
	v_pk_add_f32 v[230:231], v[104:105], v[230:231]
	v_pk_add_f32 v[228:229], v[106:107], v[228:229]
	v_pk_add_f32 v[118:119], v[230:231], v[118:119]
	v_pk_add_f32 v[116:117], v[228:229], v[116:117]
	v_pk_add_f32 v[114:115], v[118:119], v[114:115]
	v_pk_add_f32 v[112:113], v[116:117], v[112:113]
	v_pk_add_f32 v[104:105], v[114:115], v[110:111]
	v_pk_add_f32 v[106:107], v[112:113], v[108:109]
	s_waitcnt vmcnt(4)
	v_pk_add_f32 v[246:247], v[104:105], v[246:247]
	v_pk_add_f32 v[244:245], v[106:107], v[244:245]
	v_pk_add_f32 v[242:243], v[246:247], v[242:243]
	v_pk_add_f32 v[240:241], v[244:245], v[240:241]
	v_pk_add_f32 v[238:239], v[242:243], v[238:239]
	v_pk_add_f32 v[236:237], v[240:241], v[236:237]
	v_pk_add_f32 v[104:105], v[238:239], v[234:235]
	v_pk_add_f32 v[106:107], v[236:237], v[232:233]
	s_waitcnt vmcnt(0)
	v_pk_add_f32 v[100:101], v[104:105], v[100:101]
	v_pk_add_f32 v[98:99], v[106:107], v[98:99]
	v_pk_add_f32 v[96:97], v[100:101], v[96:97]
	v_pk_add_f32 v[94:95], v[98:99], v[94:95]
	v_pk_add_f32 v[92:93], v[96:97], v[92:93]
	v_pk_add_f32 v[90:91], v[94:95], v[90:91]
	v_pk_add_f32 v[74:75], v[92:93], v[74:75]
	v_pk_add_f32 v[72:73], v[90:91], v[72:73]
